# prologue modulation GEMV: 16 weight loads in flight per trip (was 4; 32 -> 8 dependent HBM round trips), same k order
# baseline (speedup 1.0000x reference)
; __device__ __forceinline__ void phase_prologue(const Params& p, unsigned char* lds) {
;     ...
;         const int l = blockIdx.x / 48, cb = blockIdx.x % 48, col = cb * 64 + lane;
;         const float* W = p.in[I_WMOD] + (size_t)l * 1024 * 3072;
;         float a[9];
; #pragma unroll
;         for (int v = 0; v < 9; ++v) a[v] = 0.f;
;         for (int k = wave * 128; k < wave * 128 + 128; ++k) { const float w = W[(size_t)k * 3072 + col];
; #pragma unroll
;             for (int v = 0; v < 9; ++v) a[v] += sc[v * 1024 + k] * w; }
.Lmods_gemv:
	v_lshl_add_u64 v[16:17], v[4:5], 0, s[0:1]
	global_load_dword v68, v[16:17], off
	s_mov_b32 s2, 0x3000
	v_add_co_u32_e32 v18, vcc, s2, v16
	s_nop 1
	v_addc_co_u32_e32 v19, vcc, 0, v17, vcc
	global_load_dword v70, v[18:19], off
	s_mov_b32 s2, 0x6000
	v_add_co_u32_e32 v18, vcc, s2, v16
	s_nop 1
	v_addc_co_u32_e32 v19, vcc, 0, v17, vcc
	global_load_dword v72, v[18:19], off
	s_mov_b32 s2, 0x9000
	v_add_co_u32_e32 v18, vcc, s2, v16
	s_nop 1
	v_addc_co_u32_e32 v19, vcc, 0, v17, vcc
	global_load_dword v74, v[18:19], off
	s_mov_b32 s2, 0xc000
	v_add_co_u32_e32 v18, vcc, s2, v16
	s_nop 1
	v_addc_co_u32_e32 v19, vcc, 0, v17, vcc
	global_load_dword v76, v[18:19], off
	s_mov_b32 s2, 0xf000
	v_add_co_u32_e32 v18, vcc, s2, v16
	s_nop 1
	v_addc_co_u32_e32 v19, vcc, 0, v17, vcc
	global_load_dword v78, v[18:19], off
	s_mov_b32 s2, 0x12000
	v_add_co_u32_e32 v18, vcc, s2, v16
	s_nop 1
	v_addc_co_u32_e32 v19, vcc, 0, v17, vcc
	global_load_dword v80, v[18:19], off
	s_mov_b32 s2, 0x15000
	v_add_co_u32_e32 v18, vcc, s2, v16
	s_nop 1
	v_addc_co_u32_e32 v19, vcc, 0, v17, vcc
	global_load_dword v82, v[18:19], off
	s_mov_b32 s2, 0x18000
	v_add_co_u32_e32 v18, vcc, s2, v16
	s_nop 1
	v_addc_co_u32_e32 v19, vcc, 0, v17, vcc
	global_load_dword v84, v[18:19], off
	s_mov_b32 s2, 0x1b000
	v_add_co_u32_e32 v18, vcc, s2, v16
	s_nop 1
	v_addc_co_u32_e32 v19, vcc, 0, v17, vcc
	global_load_dword v86, v[18:19], off
	s_mov_b32 s2, 0x1e000
	v_add_co_u32_e32 v18, vcc, s2, v16
	s_nop 1
	v_addc_co_u32_e32 v19, vcc, 0, v17, vcc
	global_load_dword v88, v[18:19], off
	s_mov_b32 s2, 0x21000
	v_add_co_u32_e32 v18, vcc, s2, v16
	s_nop 1
	v_addc_co_u32_e32 v19, vcc, 0, v17, vcc
	global_load_dword v90, v[18:19], off
	s_mov_b32 s2, 0x24000
	v_add_co_u32_e32 v18, vcc, s2, v16
	s_nop 1
	v_addc_co_u32_e32 v19, vcc, 0, v17, vcc
	global_load_dword v92, v[18:19], off
	s_mov_b32 s2, 0x27000
	v_add_co_u32_e32 v18, vcc, s2, v16
	s_nop 1
	v_addc_co_u32_e32 v19, vcc, 0, v17, vcc
	global_load_dword v94, v[18:19], off
	s_mov_b32 s2, 0x2a000
	v_add_co_u32_e32 v18, vcc, s2, v16
	s_nop 1
	v_addc_co_u32_e32 v19, vcc, 0, v17, vcc
	global_load_dword v96, v[18:19], off
	s_mov_b32 s2, 0x2d000
	v_add_co_u32_e32 v18, vcc, s2, v16
	s_nop 1
	v_addc_co_u32_e32 v19, vcc, 0, v17, vcc
	global_load_dword v98, v[18:19], off
	s_add_u32 s0, s0, 0x30000
	s_addc_u32 s1, s1, 0
	ds_read_b128 v[16:19], v0 offset:4096
	ds_read_b128 v[20:23], v0 offset:8192
	ds_read_b128 v[24:27], v0 offset:12288
	ds_read_b128 v[28:31], v0 offset:16384
	ds_read_b128 v[32:35], v0 offset:20480
	ds_read_b128 v[36:39], v0 offset:24576
	ds_read_b128 v[40:43], v0 offset:28672
	ds_read_b128 v[44:47], v0
	ds_read_b128 v[48:51], v0 offset:32768
	s_waitcnt lgkmcnt(8)
	v_mov_b32_e32 v61, v16
	s_waitcnt lgkmcnt(7)
	v_mov_b32_e32 v62, v20
	s_waitcnt lgkmcnt(6)
	v_mov_b32_e32 v63, v24
	s_waitcnt lgkmcnt(1)
	v_mov_b32_e32 v60, v44
	v_mov_b32_e32 v64, v28
	v_mov_b32_e32 v65, v32
	v_mov_b32_e32 v66, v36
	v_mov_b32_e32 v67, v40
	v_mov_b32_e32 v16, v45
	v_mov_b32_e32 v24, v21
	v_mov_b32_e32 v32, v29
	v_mov_b32_e32 v40, v37
	v_mov_b32_e32 v20, v46
	v_mov_b32_e32 v21, v18
	v_mov_b32_e32 v28, v22
	v_mov_b32_e32 v29, v26
	v_mov_b32_e32 v36, v30
	v_mov_b32_e32 v37, v34
	v_mov_b32_e32 v44, v38
	v_mov_b32_e32 v45, v42
	v_mov_b32_e32 v18, v47
	v_mov_b32_e32 v26, v23
	v_mov_b32_e32 v34, v31
	v_mov_b32_e32 v42, v39
	v_add_u32_e32 v0, 16, v0
	s_waitcnt vmcnt(15)
	v_pk_fma_f32 v[6:7], v[68:69], v[60:61], v[6:7] op_sel_hi:[0,1,1]
	v_pk_fma_f32 v[8:9], v[68:69], v[62:63], v[8:9] op_sel_hi:[0,1,1]
	v_pk_fma_f32 v[10:11], v[68:69], v[64:65], v[10:11] op_sel_hi:[0,1,1]
	v_pk_fma_f32 v[12:13], v[68:69], v[66:67], v[12:13] op_sel_hi:[0,1,1]
	s_waitcnt lgkmcnt(0)
	v_fmac_f32_e32 v15, v68, v48
	s_waitcnt vmcnt(14)
	v_pk_fma_f32 v[6:7], v[70:71], v[16:17], v[6:7] op_sel_hi:[0,1,1]
	v_pk_fma_f32 v[8:9], v[70:71], v[24:25], v[8:9] op_sel_hi:[0,1,1]
	v_pk_fma_f32 v[10:11], v[70:71], v[32:33], v[10:11] op_sel_hi:[0,1,1]
	v_pk_fma_f32 v[12:13], v[70:71], v[40:41], v[12:13] op_sel_hi:[0,1,1]
	v_fmac_f32_e32 v15, v70, v49
	s_waitcnt vmcnt(13)
	v_pk_fma_f32 v[6:7], v[72:73], v[20:21], v[6:7] op_sel_hi:[0,1,1]
	v_pk_fma_f32 v[8:9], v[72:73], v[28:29], v[8:9] op_sel_hi:[0,1,1]
	v_pk_fma_f32 v[10:11], v[72:73], v[36:37], v[10:11] op_sel_hi:[0,1,1]
	v_pk_fma_f32 v[12:13], v[72:73], v[44:45], v[12:13] op_sel_hi:[0,1,1]
	v_fmac_f32_e32 v15, v72, v50
	s_waitcnt vmcnt(12)
	v_pk_fma_f32 v[6:7], v[74:75], v[18:19], v[6:7] op_sel_hi:[0,1,1]
	v_pk_fma_f32 v[8:9], v[74:75], v[26:27], v[8:9] op_sel_hi:[0,1,1]
	v_pk_fma_f32 v[10:11], v[74:75], v[34:35], v[10:11] op_sel_hi:[0,1,1]
	v_pk_fma_f32 v[12:13], v[74:75], v[42:43], v[12:13] op_sel_hi:[0,1,1]
	v_fmac_f32_e32 v15, v74, v51
	ds_read_b128 v[16:19], v0 offset:4096
	ds_read_b128 v[20:23], v0 offset:8192
	ds_read_b128 v[24:27], v0 offset:12288
	ds_read_b128 v[28:31], v0 offset:16384
	ds_read_b128 v[32:35], v0 offset:20480
	ds_read_b128 v[36:39], v0 offset:24576
	ds_read_b128 v[40:43], v0 offset:28672
	ds_read_b128 v[44:47], v0
	ds_read_b128 v[48:51], v0 offset:32768
	s_waitcnt lgkmcnt(8)
	v_mov_b32_e32 v61, v16
	s_waitcnt lgkmcnt(7)
	v_mov_b32_e32 v62, v20
	s_waitcnt lgkmcnt(6)
	v_mov_b32_e32 v63, v24
	s_waitcnt lgkmcnt(1)
	v_mov_b32_e32 v60, v44
	v_mov_b32_e32 v64, v28
	v_mov_b32_e32 v65, v32
	v_mov_b32_e32 v66, v36
	v_mov_b32_e32 v67, v40
	v_mov_b32_e32 v16, v45
	v_mov_b32_e32 v24, v21
	v_mov_b32_e32 v32, v29
	v_mov_b32_e32 v40, v37
	v_mov_b32_e32 v20, v46
	v_mov_b32_e32 v21, v18
	v_mov_b32_e32 v28, v22
	v_mov_b32_e32 v29, v26
	v_mov_b32_e32 v36, v30
	v_mov_b32_e32 v37, v34
	v_mov_b32_e32 v44, v38
	v_mov_b32_e32 v45, v42
	v_mov_b32_e32 v18, v47
	v_mov_b32_e32 v26, v23
	v_mov_b32_e32 v34, v31
	v_mov_b32_e32 v42, v39
	v_add_u32_e32 v0, 16, v0
	s_waitcnt vmcnt(11)
; __device__ __forceinline__ void phase_prologue(const Params& p, unsigned char* lds) {
;     ...
;         for (int k = wave * 128; k < wave * 128 + 128; ++k) { const float w = W[(size_t)k * 3072 + col];
; #pragma unroll
;             for (int v = 0; v < 9; ++v) a[v] += sc[v * 1024 + k] * w; }
	v_pk_fma_f32 v[6:7], v[76:77], v[60:61], v[6:7] op_sel_hi:[0,1,1]
	v_pk_fma_f32 v[8:9], v[76:77], v[62:63], v[8:9] op_sel_hi:[0,1,1]
	v_pk_fma_f32 v[10:11], v[76:77], v[64:65], v[10:11] op_sel_hi:[0,1,1]
	v_pk_fma_f32 v[12:13], v[76:77], v[66:67], v[12:13] op_sel_hi:[0,1,1]
	s_waitcnt lgkmcnt(0)
	v_fmac_f32_e32 v15, v76, v48
	s_waitcnt vmcnt(10)
	v_pk_fma_f32 v[6:7], v[78:79], v[16:17], v[6:7] op_sel_hi:[0,1,1]
	v_pk_fma_f32 v[8:9], v[78:79], v[24:25], v[8:9] op_sel_hi:[0,1,1]
	v_pk_fma_f32 v[10:11], v[78:79], v[32:33], v[10:11] op_sel_hi:[0,1,1]
	v_pk_fma_f32 v[12:13], v[78:79], v[40:41], v[12:13] op_sel_hi:[0,1,1]
	v_fmac_f32_e32 v15, v78, v49
	s_waitcnt vmcnt(9)
	v_pk_fma_f32 v[6:7], v[80:81], v[20:21], v[6:7] op_sel_hi:[0,1,1]
	v_pk_fma_f32 v[8:9], v[80:81], v[28:29], v[8:9] op_sel_hi:[0,1,1]
	v_pk_fma_f32 v[10:11], v[80:81], v[36:37], v[10:11] op_sel_hi:[0,1,1]
	v_pk_fma_f32 v[12:13], v[80:81], v[44:45], v[12:13] op_sel_hi:[0,1,1]
	v_fmac_f32_e32 v15, v80, v50
	s_waitcnt vmcnt(8)
	v_pk_fma_f32 v[6:7], v[82:83], v[18:19], v[6:7] op_sel_hi:[0,1,1]
	v_pk_fma_f32 v[8:9], v[82:83], v[26:27], v[8:9] op_sel_hi:[0,1,1]
	v_pk_fma_f32 v[10:11], v[82:83], v[34:35], v[10:11] op_sel_hi:[0,1,1]
	v_pk_fma_f32 v[12:13], v[82:83], v[42:43], v[12:13] op_sel_hi:[0,1,1]
	v_fmac_f32_e32 v15, v82, v51
	ds_read_b128 v[16:19], v0 offset:4096
	ds_read_b128 v[20:23], v0 offset:8192
	ds_read_b128 v[24:27], v0 offset:12288
	ds_read_b128 v[28:31], v0 offset:16384
	ds_read_b128 v[32:35], v0 offset:20480
	ds_read_b128 v[36:39], v0 offset:24576
	ds_read_b128 v[40:43], v0 offset:28672
	ds_read_b128 v[44:47], v0
	ds_read_b128 v[48:51], v0 offset:32768
	s_waitcnt lgkmcnt(8)
	v_mov_b32_e32 v61, v16
	s_waitcnt lgkmcnt(7)
	v_mov_b32_e32 v62, v20
	s_waitcnt lgkmcnt(6)
	v_mov_b32_e32 v63, v24
	s_waitcnt lgkmcnt(1)
	v_mov_b32_e32 v60, v44
	v_mov_b32_e32 v64, v28
	v_mov_b32_e32 v65, v32
	v_mov_b32_e32 v66, v36
	v_mov_b32_e32 v67, v40
	v_mov_b32_e32 v16, v45
	v_mov_b32_e32 v24, v21
	v_mov_b32_e32 v32, v29
	v_mov_b32_e32 v40, v37
	v_mov_b32_e32 v20, v46
	v_mov_b32_e32 v21, v18
	v_mov_b32_e32 v28, v22
	v_mov_b32_e32 v29, v26
	v_mov_b32_e32 v36, v30
	v_mov_b32_e32 v37, v34
	v_mov_b32_e32 v44, v38
	v_mov_b32_e32 v45, v42
	v_mov_b32_e32 v18, v47
	v_mov_b32_e32 v26, v23
	v_mov_b32_e32 v34, v31
	v_mov_b32_e32 v42, v39
	v_add_u32_e32 v0, 16, v0
	s_waitcnt vmcnt(7)
	v_pk_fma_f32 v[6:7], v[84:85], v[60:61], v[6:7] op_sel_hi:[0,1,1]
	v_pk_fma_f32 v[8:9], v[84:85], v[62:63], v[8:9] op_sel_hi:[0,1,1]
	v_pk_fma_f32 v[10:11], v[84:85], v[64:65], v[10:11] op_sel_hi:[0,1,1]
	v_pk_fma_f32 v[12:13], v[84:85], v[66:67], v[12:13] op_sel_hi:[0,1,1]
	s_waitcnt lgkmcnt(0)
	v_fmac_f32_e32 v15, v84, v48
	s_waitcnt vmcnt(6)
	v_pk_fma_f32 v[6:7], v[86:87], v[16:17], v[6:7] op_sel_hi:[0,1,1]
	v_pk_fma_f32 v[8:9], v[86:87], v[24:25], v[8:9] op_sel_hi:[0,1,1]
	v_pk_fma_f32 v[10:11], v[86:87], v[32:33], v[10:11] op_sel_hi:[0,1,1]
	v_pk_fma_f32 v[12:13], v[86:87], v[40:41], v[12:13] op_sel_hi:[0,1,1]
	v_fmac_f32_e32 v15, v86, v49
	s_waitcnt vmcnt(5)
	v_pk_fma_f32 v[6:7], v[88:89], v[20:21], v[6:7] op_sel_hi:[0,1,1]
	v_pk_fma_f32 v[8:9], v[88:89], v[28:29], v[8:9] op_sel_hi:[0,1,1]
	v_pk_fma_f32 v[10:11], v[88:89], v[36:37], v[10:11] op_sel_hi:[0,1,1]
	v_pk_fma_f32 v[12:13], v[88:89], v[44:45], v[12:13] op_sel_hi:[0,1,1]
	v_fmac_f32_e32 v15, v88, v50
	s_waitcnt vmcnt(4)
	v_pk_fma_f32 v[6:7], v[90:91], v[18:19], v[6:7] op_sel_hi:[0,1,1]
	v_pk_fma_f32 v[8:9], v[90:91], v[26:27], v[8:9] op_sel_hi:[0,1,1]
	v_pk_fma_f32 v[10:11], v[90:91], v[34:35], v[10:11] op_sel_hi:[0,1,1]
	v_pk_fma_f32 v[12:13], v[90:91], v[42:43], v[12:13] op_sel_hi:[0,1,1]
	v_fmac_f32_e32 v15, v90, v51
	ds_read_b128 v[16:19], v0 offset:4096
	ds_read_b128 v[20:23], v0 offset:8192
	ds_read_b128 v[24:27], v0 offset:12288
	ds_read_b128 v[28:31], v0 offset:16384
	ds_read_b128 v[32:35], v0 offset:20480
	ds_read_b128 v[36:39], v0 offset:24576
	ds_read_b128 v[40:43], v0 offset:28672
	ds_read_b128 v[44:47], v0
	ds_read_b128 v[48:51], v0 offset:32768
	s_waitcnt lgkmcnt(8)
	v_mov_b32_e32 v61, v16
	s_waitcnt lgkmcnt(7)
	v_mov_b32_e32 v62, v20
	s_waitcnt lgkmcnt(6)
	v_mov_b32_e32 v63, v24
	s_waitcnt lgkmcnt(1)
	v_mov_b32_e32 v60, v44
	v_mov_b32_e32 v64, v28
	v_mov_b32_e32 v65, v32
	v_mov_b32_e32 v66, v36
	v_mov_b32_e32 v67, v40
	v_mov_b32_e32 v16, v45
	v_mov_b32_e32 v24, v21
	v_mov_b32_e32 v32, v29
	v_mov_b32_e32 v40, v37
	v_mov_b32_e32 v20, v46
	v_mov_b32_e32 v21, v18
	v_mov_b32_e32 v28, v22
	v_mov_b32_e32 v29, v26
	v_mov_b32_e32 v36, v30
	v_mov_b32_e32 v37, v34
	v_mov_b32_e32 v44, v38
	v_mov_b32_e32 v45, v42
	v_mov_b32_e32 v18, v47
	v_mov_b32_e32 v26, v23
	v_mov_b32_e32 v34, v31
	v_mov_b32_e32 v42, v39
	v_add_u32_e32 v0, 16, v0
	s_waitcnt vmcnt(3)
	v_pk_fma_f32 v[6:7], v[92:93], v[60:61], v[6:7] op_sel_hi:[0,1,1]
	v_pk_fma_f32 v[8:9], v[92:93], v[62:63], v[8:9] op_sel_hi:[0,1,1]
	v_pk_fma_f32 v[10:11], v[92:93], v[64:65], v[10:11] op_sel_hi:[0,1,1]
	v_pk_fma_f32 v[12:13], v[92:93], v[66:67], v[12:13] op_sel_hi:[0,1,1]
	s_waitcnt lgkmcnt(0)
	v_fmac_f32_e32 v15, v92, v48
	s_waitcnt vmcnt(2)
	v_pk_fma_f32 v[6:7], v[94:95], v[16:17], v[6:7] op_sel_hi:[0,1,1]
	v_pk_fma_f32 v[8:9], v[94:95], v[24:25], v[8:9] op_sel_hi:[0,1,1]
	v_pk_fma_f32 v[10:11], v[94:95], v[32:33], v[10:11] op_sel_hi:[0,1,1]
	v_pk_fma_f32 v[12:13], v[94:95], v[40:41], v[12:13] op_sel_hi:[0,1,1]
	v_fmac_f32_e32 v15, v94, v49
	s_waitcnt vmcnt(1)
	v_pk_fma_f32 v[6:7], v[96:97], v[20:21], v[6:7] op_sel_hi:[0,1,1]
	v_pk_fma_f32 v[8:9], v[96:97], v[28:29], v[8:9] op_sel_hi:[0,1,1]
	v_pk_fma_f32 v[10:11], v[96:97], v[36:37], v[10:11] op_sel_hi:[0,1,1]
	v_pk_fma_f32 v[12:13], v[96:97], v[44:45], v[12:13] op_sel_hi:[0,1,1]
	v_fmac_f32_e32 v15, v96, v50
	s_waitcnt vmcnt(0)
	v_pk_fma_f32 v[6:7], v[98:99], v[18:19], v[6:7] op_sel_hi:[0,1,1]
	v_pk_fma_f32 v[8:9], v[98:99], v[26:27], v[8:9] op_sel_hi:[0,1,1]
	v_pk_fma_f32 v[10:11], v[98:99], v[34:35], v[10:11] op_sel_hi:[0,1,1]
	v_pk_fma_f32 v[12:13], v[98:99], v[42:43], v[12:13] op_sel_hi:[0,1,1]
	v_fmac_f32_e32 v15, v98, v51
	s_cmp_eq_u32 s0, 0x180000
	s_cbranch_scc0 .Lmods_gemv
; __device__ __forceinline__ void phase_prologue(const Params& p, unsigned char* lds) {
;     ...
;         for (int v = 0; v < 9; ++v) red[(wave * 9 + v) * 64 + lane] = a[v];
;         __syncthreads();
;         for (int i = tid; i < 9 * 64; i += 512) { const int v = i >> 6, cl = i & 63; float s = 0.f;
; #pragma unroll
;             for (int w = 0; w < 8; ++w) s += red[(w * 9 + v) * 64 + cl];
;             mods[((size_t)l * 9 + v) * 3072 + cb * 64 + cl] = s + p.in[I_BMOD][l * 3072 + cb * 64 + cl]; }
	v_lshl_add_u32 v0, v3, 2, 0
	s_movk_i32 s0, 0x900
	v_mad_u64_u32 v[4:5], s[0:1], v14, s0, v[0:1]
	s_movk_i32 s0, 0x240
	s_nop 0
	v_cmp_gt_i32_e32 vcc, s0, v2
	ds_write2st64_b32 v4, v6, v7 offset0:144 offset1:145
	ds_write2st64_b32 v4, v8, v9 offset0:146 offset1:147
	ds_write2st64_b32 v4, v10, v11 offset0:148 offset1:149
	ds_write2st64_b32 v4, v12, v13 offset0:150 offset1:151
	ds_write_b32 v4, v15 offset:38912
	s_waitcnt lgkmcnt(0)
	s_barrier
	s_and_saveexec_b64 s[0:1], vcc
	v_readlane_b32 s20, v252, 50
	s_cbranch_execz .LBB0_1327
	v_readlane_b32 s4, v253, 12
	v_readlane_b32 s2, v250, 36
	v_readlane_b32 s5, v253, 13
	v_readlane_b32 s4, v250, 39
	v_or_b32_e32 v4, s2, v3
	v_lshlrev_b32_e32 v4, 2, v4
	v_mov_b32_e32 v5, v1
	v_readlane_b32 s14, v253, 22
	v_readlane_b32 s15, v253, 23
	v_lshlrev_b32_e32 v6, 2, v3
	v_mov_b32_e32 v7, v1
	v_readlane_b32 s5, v250, 40
	v_lshl_add_u64 v[4:5], s[14:15], 0, v[4:5]
	v_readlane_b32 s6, v253, 14
	v_lshl_add_u64 v[6:7], s[4:5], 0, v[6:7]
	s_mov_b64 s[4:5], 0
	v_readlane_b32 s7, v253, 15
	v_readlane_b32 s8, v253, 16
	v_readlane_b32 s9, v253, 17
	v_readlane_b32 s10, v253, 18
	v_readlane_b32 s11, v253, 19
	v_readlane_b32 s12, v253, 20
	v_readlane_b32 s13, v253, 21
	v_readlane_b32 s16, v253, 24
	v_readlane_b32 s17, v253, 25
	v_readlane_b32 s18, v253, 26
	v_readlane_b32 s19, v253, 27
